# static s_setprio 3 (was 1) for waves 4-7
# baseline (speedup 1.0000x reference)
; #define LAS __attribute__((address_space(3)))
; __global__ void __launch_bounds__(NTHR, 2) hybrid_fwd(Params p) {
;     extern __shared__ __attribute__((aligned(16))) unsigned char lds_raw[];
;     LAS unsigned char* lds = (LAS unsigned char*)lds_raw;
_Z10hybrid_fwd6Params:
	v_readfirstlane_b32 s98, v0
	s_nop 3
	s_and_b32 s98, s98, 0x3ff
	s_lshr_b32 s98, s98, 6
	s_cmp_ge_u32 s98, 4
	s_cbranch_scc0 .Lprio_done
	s_setprio 3
